# speedup vs baseline: 1.0098x; 1.0086x over previous
; __device__ __forceinline__ unsigned cvt_pk_bf16(float lo, float hi) { unsigned r; asm volatile("v_cvt_pk_bf16_f32 %0, %1, %2" : "=v"(r) : "v"(lo), "v"(hi)); return r; }
;     __device__ __forceinline__ void operator()(const f32x4 (&acc)[2][2][4][2], const Unit& u, int wr, int wc, int fr, int fq) const {
;     ...
;         const int col0 = u.pn * HALF + wc * 32 + 8 * fq;
; #pragma unroll
;         for (int ai = 0; ai < 2; ++ai)
; #pragma unroll
;             for (int m = 0; m < 4; ++m) { bf16_t* rowp = O + (size_t)(row0 + ai * HALF + m * 16) * ldc + col0;
;                 f32x2 h[4];
; #pragma unroll
;                 for (int n = 0; n < 2; ++n)
; #pragma unroll
;                     for (int j = 0; j < 2; ++j) { const f32x2 g = {acc[ai][0][m][n][2 * j], acc[ai][0][m][n][2 * j + 1]}, up = {acc[ai][1][m][n][2 * j], acc[ai][1][m][n][2 * j + 1]};
;                         const f32x2 t = g * (-1.44269504089f); f32x2 e; e.x = __builtin_amdgcn_exp2f(t.x); e.y = __builtin_amdgcn_exp2f(t.y);
;                         const f32x2 d = e + 1.0f; f32x2 r; r.x = __builtin_amdgcn_rcpf(d.x); r.y = __builtin_amdgcn_rcpf(d.y);
;                         h[n * 2 + j] = (g * r) * up; }
;                 u32x4 w; w.x = cvt_pk_bf16(h[0].x, h[0].y); w.y = cvt_pk_bf16(h[1].x, h[1].y); w.z = cvt_pk_bf16(h[2].x, h[2].y); w.w = cvt_pk_bf16(h[3].x, h[3].y);
;                 *(u32x4*)rowp = w; }
.LBB0_362:
	v_lshrrev_b32_e32 v254, 2, v206
	v_and_b32_e32 v255, 15, v206
	v_sub_u32_e32 v252, v254, v255
	v_mul_lo_u32 v252, v252, s20
	v_lshlrev_b32_e32 v252, 1, v252
	v_and_b32_e32 v253, 3, v206
	v_lshrrev_b32_e32 v255, 4, v206
	v_sub_u32_e32 v253, v253, v255
	v_lshl_add_u32 v252, v253, 4, v252
	v_ashrrev_i32_e32 v253, 31, v252
	v_lshrrev_b32_e32 v255, 6, v180
	v_mul_u32_u24_e32 v255, 0x500, v255
	v_add_u32_e32 v255, 0x20000, v255
	v_and_b32_e32 v244, 15, v206
	v_mul_u32_u24_e32 v244, 0x50, v244
	v_lshrrev_b32_e32 v245, 4, v206
	v_lshl_add_u32 v244, v245, 4, v244
	v_add_u32_e32 v244, v244, v255
	v_mul_u32_u24_e32 v245, 0x50, v254
	v_and_b32_e32 v254, 3, v206
	v_lshl_add_u32 v245, v254, 4, v245
	v_add_u32_e32 v245, v245, v255
	v_lshl_add_u32 v148, s31, 8, v144
	s_cmp_lt_i32 s30, 0
	s_mov_b64 s[38:39], -1
	s_mov_b32 s60, 0x14000
	s_cbranch_scc0 .LBB0_369
	v_mad_i64_i32 v[140:141], s[18:19], s20, v148, 0
	v_lshl_add_u64 v[140:141], v[140:141], 1, s[8:9]
	s_and_b64 vcc, exec, s[26:27]
	v_or_b32_e32 v155, 16, v148
	v_or_b32_e32 v154, 32, v148
	v_or_b32_e32 v153, 48, v148
	v_add_u32_e32 v152, 0x80, v148
	v_add_u32_e32 v151, 0x90, v148
	v_add_u32_e32 v150, 0xa0, v148
	v_add_u32_e32 v149, 0xb0, v148
	s_cbranch_vccz .LBB0_365
	v_pk_mul_f32 v[156:157], v[126:127], s[92:93] op_sel_hi:[1,0]
	v_pk_mul_f32 v[158:159], v[128:129], s[92:93] op_sel_hi:[1,0]
	v_exp_f32_e32 v156, v156
	v_exp_f32_e32 v157, v157
	v_exp_f32_e32 v158, v158
	v_exp_f32_e32 v159, v159
	v_pk_mul_f32 v[160:161], v[122:123], s[92:93] op_sel_hi:[1,0]
	v_pk_mul_f32 v[162:163], v[124:125], s[92:93] op_sel_hi:[1,0]
	v_exp_f32_e32 v160, v160
	v_exp_f32_e32 v161, v161
	v_exp_f32_e32 v162, v162
	v_exp_f32_e32 v163, v163
	v_pk_add_f32 v[156:157], v[156:157], 1.0 op_sel_hi:[1,0]
	v_pk_add_f32 v[158:159], v[158:159], 1.0 op_sel_hi:[1,0]
	v_rcp_f32_e32 v156, v156
	v_rcp_f32_e32 v157, v157
	v_rcp_f32_e32 v158, v158
	v_rcp_f32_e32 v159, v159
	v_pk_add_f32 v[160:161], v[160:161], 1.0 op_sel_hi:[1,0]
	v_pk_add_f32 v[162:163], v[162:163], 1.0 op_sel_hi:[1,0]
	v_rcp_f32_e32 v160, v160
	v_rcp_f32_e32 v161, v161
	v_rcp_f32_e32 v162, v162
	v_rcp_f32_e32 v163, v163
	v_lshl_or_b32 v142, s67, 7, v146
	v_ashrrev_i32_e32 v143, 31, v142
	v_pk_mul_f32 v[156:157], v[126:127], v[156:157]
	v_pk_mul_f32 v[158:159], v[128:129], v[158:159]
	v_pk_mul_f32 v[156:157], v[114:115], v[156:157]
	v_pk_mul_f32 v[158:159], v[116:117], v[158:159]
	v_pk_mul_f32 v[160:161], v[122:123], v[160:161]
	v_pk_mul_f32 v[162:163], v[124:125], v[162:163]
	v_lshlrev_b64 v[142:143], 1, v[142:143]
	v_pk_mul_f32 v[160:161], v[106:107], v[160:161]
	v_pk_mul_f32 v[162:163], v[108:109], v[162:163]
	v_lshl_add_u64 v[164:165], v[140:141], 0, v[142:143]
	v_cvt_pk_bf16_f32 v156, v156, v157
	v_cvt_pk_bf16_f32 v157, v158, v159
	v_cvt_pk_bf16_f32 v158, v160, v161
	v_cvt_pk_bf16_f32 v159, v162, v163
	ds_write_b128 v244, v[156:159]
	v_lshl_add_u64 v[176:177], v[164:165], 0, v[252:253]
	ds_read_b128 v[168:171], v245
	v_pk_mul_f32 v[160:161], v[120:121], s[92:93] op_sel_hi:[1,0]
	v_pk_mul_f32 v[162:163], v[110:111], s[92:93] op_sel_hi:[1,0]
	v_pk_mul_f32 v[158:159], v[118:119], s[92:93] op_sel_hi:[1,0]
	v_pk_mul_f32 v[164:165], v[112:113], s[92:93] op_sel_hi:[1,0]
	v_exp_f32_e32 v158, v158
	v_exp_f32_e32 v159, v159
	v_exp_f32_e32 v160, v160
	v_exp_f32_e32 v161, v161
	v_exp_f32_e32 v162, v162
	v_exp_f32_e32 v163, v163
	v_exp_f32_e32 v164, v164
	v_exp_f32_e32 v165, v165
	v_pk_add_f32 v[158:159], v[158:159], 1.0 op_sel_hi:[1,0]
	v_pk_add_f32 v[160:161], v[160:161], 1.0 op_sel_hi:[1,0]
	v_rcp_f32_e32 v158, v158
	v_rcp_f32_e32 v159, v159
	v_pk_add_f32 v[162:163], v[162:163], 1.0 op_sel_hi:[1,0]
	v_pk_add_f32 v[164:165], v[164:165], 1.0 op_sel_hi:[1,0]
	v_rcp_f32_e32 v160, v160
	v_rcp_f32_e32 v161, v161
	v_rcp_f32_e32 v162, v162
	v_rcp_f32_e32 v163, v163
	v_rcp_f32_e32 v164, v164
	v_rcp_f32_e32 v165, v165
	v_mad_i64_i32 v[156:157], s[18:19], s20, v155, 0
	v_pk_mul_f32 v[158:159], v[118:119], v[158:159]
	v_lshl_add_u64 v[156:157], v[156:157], 1, s[8:9]
	v_pk_mul_f32 v[158:159], v[98:99], v[158:159]
	v_pk_mul_f32 v[160:161], v[120:121], v[160:161]
	v_pk_mul_f32 v[162:163], v[110:111], v[162:163]
	v_pk_mul_f32 v[164:165], v[112:113], v[164:165]
	v_pk_mul_f32 v[160:161], v[100:101], v[160:161]
	v_pk_mul_f32 v[162:163], v[90:91], v[162:163]
	v_pk_mul_f32 v[164:165], v[92:93], v[164:165]
	v_lshl_add_u64 v[166:167], v[156:157], 0, v[142:143]
	v_cvt_pk_bf16_f32 v156, v158, v159
	v_cvt_pk_bf16_f32 v157, v160, v161
	v_cvt_pk_bf16_f32 v158, v162, v163
	v_cvt_pk_bf16_f32 v159, v164, v165
	ds_write_b128 v244, v[156:159]
	v_lshl_add_u64 v[178:179], v[166:167], 0, v[252:253]
	ds_read_b128 v[172:175], v245
	v_pk_mul_f32 v[160:161], v[104:105], s[92:93] op_sel_hi:[1,0]
	v_pk_mul_f32 v[162:163], v[94:95], s[92:93] op_sel_hi:[1,0]
	v_pk_mul_f32 v[158:159], v[102:103], s[92:93] op_sel_hi:[1,0]
	v_pk_mul_f32 v[164:165], v[96:97], s[92:93] op_sel_hi:[1,0]
	v_exp_f32_e32 v158, v158
	v_exp_f32_e32 v159, v159
	v_exp_f32_e32 v160, v160
	v_exp_f32_e32 v161, v161
	v_exp_f32_e32 v162, v162
	v_exp_f32_e32 v163, v163
	v_exp_f32_e32 v164, v164
	v_exp_f32_e32 v165, v165
	v_pk_add_f32 v[158:159], v[158:159], 1.0 op_sel_hi:[1,0]
	v_pk_add_f32 v[160:161], v[160:161], 1.0 op_sel_hi:[1,0]
	v_rcp_f32_e32 v158, v158
	v_rcp_f32_e32 v159, v159
	v_pk_add_f32 v[162:163], v[162:163], 1.0 op_sel_hi:[1,0]
	v_pk_add_f32 v[164:165], v[164:165], 1.0 op_sel_hi:[1,0]
	v_rcp_f32_e32 v160, v160
	v_rcp_f32_e32 v161, v161
	v_rcp_f32_e32 v162, v162
	v_rcp_f32_e32 v163, v163
	v_rcp_f32_e32 v164, v164
	v_rcp_f32_e32 v165, v165
	v_mad_i64_i32 v[156:157], s[18:19], s20, v154, 0
	v_pk_mul_f32 v[158:159], v[102:103], v[158:159]
	v_lshl_add_u64 v[156:157], v[156:157], 1, s[8:9]
	v_pk_mul_f32 v[158:159], v[82:83], v[158:159]
	v_pk_mul_f32 v[160:161], v[104:105], v[160:161]
	v_pk_mul_f32 v[162:163], v[94:95], v[162:163]
	v_pk_mul_f32 v[164:165], v[96:97], v[164:165]
	v_pk_mul_f32 v[160:161], v[84:85], v[160:161]
	v_pk_mul_f32 v[162:163], v[74:75], v[162:163]
	v_pk_mul_f32 v[164:165], v[76:77], v[164:165]
	v_lshl_add_u64 v[166:167], v[156:157], 0, v[142:143]
	v_cvt_pk_bf16_f32 v156, v158, v159
	v_cvt_pk_bf16_f32 v157, v160, v161
	v_cvt_pk_bf16_f32 v158, v162, v163
	v_cvt_pk_bf16_f32 v159, v164, v165
	ds_write_b128 v244, v[156:159]
	v_lshl_add_u64 v[186:187], v[166:167], 0, v[252:253]
	ds_read_b128 v[182:185], v245
	s_waitcnt lgkmcnt(4)
; __device__ __forceinline__ unsigned cvt_pk_bf16(float lo, float hi) { unsigned r; asm volatile("v_cvt_pk_bf16_f32 %0, %1, %2" : "=v"(r) : "v"(lo), "v"(hi)); return r; }
;     __device__ __forceinline__ void operator()(const f32x4 (&acc)[2][2][4][2], const Unit& u, int wr, int wc, int fr, int fq) const {
;     ...
;         const int col0 = u.pn * HALF + wc * 32 + 8 * fq;
; #pragma unroll
;         for (int ai = 0; ai < 2; ++ai)
; #pragma unroll
;             for (int m = 0; m < 4; ++m) { bf16_t* rowp = O + (size_t)(row0 + ai * HALF + m * 16) * ldc + col0;
;                 f32x2 h[4];
; #pragma unroll
;                 for (int n = 0; n < 2; ++n)
; #pragma unroll
;                     for (int j = 0; j < 2; ++j) { const f32x2 g = {acc[ai][0][m][n][2 * j], acc[ai][0][m][n][2 * j + 1]}, up = {acc[ai][1][m][n][2 * j], acc[ai][1][m][n][2 * j + 1]};
;                         const f32x2 t = g * (-1.44269504089f); f32x2 e; e.x = __builtin_amdgcn_exp2f(t.x); e.y = __builtin_amdgcn_exp2f(t.y);
;                         const f32x2 d = e + 1.0f; f32x2 r; r.x = __builtin_amdgcn_rcpf(d.x); r.y = __builtin_amdgcn_rcpf(d.y);
;                         h[n * 2 + j] = (g * r) * up; }
;                 u32x4 w; w.x = cvt_pk_bf16(h[0].x, h[0].y); w.y = cvt_pk_bf16(h[1].x, h[1].y); w.z = cvt_pk_bf16(h[2].x, h[2].y); w.w = cvt_pk_bf16(h[3].x, h[3].y);
;                 *(u32x4*)rowp = w; }
	global_store_dwordx4 v[176:177], v[168:171], off
	v_pk_mul_f32 v[160:161], v[88:89], s[92:93] op_sel_hi:[1,0]
	v_pk_mul_f32 v[162:163], v[78:79], s[92:93] op_sel_hi:[1,0]
	v_pk_mul_f32 v[158:159], v[86:87], s[92:93] op_sel_hi:[1,0]
	v_pk_mul_f32 v[164:165], v[80:81], s[92:93] op_sel_hi:[1,0]
	v_exp_f32_e32 v158, v158
	v_exp_f32_e32 v159, v159
	v_exp_f32_e32 v160, v160
	v_exp_f32_e32 v161, v161
	v_exp_f32_e32 v162, v162
	v_exp_f32_e32 v163, v163
	v_exp_f32_e32 v164, v164
	v_exp_f32_e32 v165, v165
	v_pk_add_f32 v[158:159], v[158:159], 1.0 op_sel_hi:[1,0]
	v_pk_add_f32 v[160:161], v[160:161], 1.0 op_sel_hi:[1,0]
	v_rcp_f32_e32 v158, v158
	v_rcp_f32_e32 v159, v159
	v_pk_add_f32 v[162:163], v[162:163], 1.0 op_sel_hi:[1,0]
	v_pk_add_f32 v[164:165], v[164:165], 1.0 op_sel_hi:[1,0]
	v_rcp_f32_e32 v160, v160
	v_rcp_f32_e32 v161, v161
	v_rcp_f32_e32 v162, v162
	v_rcp_f32_e32 v163, v163
	v_rcp_f32_e32 v164, v164
	v_rcp_f32_e32 v165, v165
	v_mad_i64_i32 v[156:157], s[18:19], s20, v153, 0
	v_pk_mul_f32 v[158:159], v[86:87], v[158:159]
	v_lshl_add_u64 v[156:157], v[156:157], 1, s[8:9]
	v_pk_mul_f32 v[158:159], v[70:71], v[158:159]
	v_pk_mul_f32 v[160:161], v[88:89], v[160:161]
	v_pk_mul_f32 v[162:163], v[78:79], v[162:163]
	v_pk_mul_f32 v[164:165], v[80:81], v[164:165]
	v_pk_mul_f32 v[160:161], v[72:73], v[160:161]
	v_pk_mul_f32 v[162:163], v[66:67], v[162:163]
	v_pk_mul_f32 v[164:165], v[68:69], v[164:165]
	v_lshl_add_u64 v[166:167], v[156:157], 0, v[142:143]
	v_cvt_pk_bf16_f32 v156, v158, v159
	v_cvt_pk_bf16_f32 v157, v160, v161
	v_cvt_pk_bf16_f32 v158, v162, v163
	v_cvt_pk_bf16_f32 v159, v164, v165
	ds_write_b128 v244, v[156:159]
	v_lshl_add_u64 v[176:177], v[166:167], 0, v[252:253]
	ds_read_b128 v[168:171], v245
	s_waitcnt lgkmcnt(4)
	global_store_dwordx4 v[178:179], v[172:175], off
	v_pk_mul_f32 v[160:161], v[64:65], s[92:93] op_sel_hi:[1,0]
	v_pk_mul_f32 v[162:163], v[58:59], s[92:93] op_sel_hi:[1,0]
	v_pk_mul_f32 v[158:159], v[62:63], s[92:93] op_sel_hi:[1,0]
	v_pk_mul_f32 v[164:165], v[60:61], s[92:93] op_sel_hi:[1,0]
	v_exp_f32_e32 v158, v158
	v_exp_f32_e32 v159, v159
	v_exp_f32_e32 v160, v160
	v_exp_f32_e32 v161, v161
	v_exp_f32_e32 v162, v162
	v_exp_f32_e32 v163, v163
	v_exp_f32_e32 v164, v164
	v_exp_f32_e32 v165, v165
	v_pk_add_f32 v[158:159], v[158:159], 1.0 op_sel_hi:[1,0]
	v_pk_add_f32 v[160:161], v[160:161], 1.0 op_sel_hi:[1,0]
	v_rcp_f32_e32 v158, v158
	v_rcp_f32_e32 v159, v159
	v_pk_add_f32 v[162:163], v[162:163], 1.0 op_sel_hi:[1,0]
	v_pk_add_f32 v[164:165], v[164:165], 1.0 op_sel_hi:[1,0]
	v_rcp_f32_e32 v160, v160
	v_rcp_f32_e32 v161, v161
	v_rcp_f32_e32 v162, v162
	v_rcp_f32_e32 v163, v163
	v_rcp_f32_e32 v164, v164
	v_rcp_f32_e32 v165, v165
	v_mad_i64_i32 v[156:157], s[18:19], s20, v152, 0
	v_pk_mul_f32 v[158:159], v[62:63], v[158:159]
	v_lshl_add_u64 v[156:157], v[156:157], 1, s[8:9]
	v_pk_mul_f32 v[158:159], v[50:51], v[158:159]
	v_pk_mul_f32 v[160:161], v[64:65], v[160:161]
	v_pk_mul_f32 v[162:163], v[58:59], v[162:163]
	v_pk_mul_f32 v[164:165], v[60:61], v[164:165]
	v_pk_mul_f32 v[160:161], v[52:53], v[160:161]
	v_pk_mul_f32 v[162:163], v[42:43], v[162:163]
	v_pk_mul_f32 v[164:165], v[44:45], v[164:165]
	v_lshl_add_u64 v[166:167], v[156:157], 0, v[142:143]
	v_cvt_pk_bf16_f32 v156, v158, v159
	v_cvt_pk_bf16_f32 v157, v160, v161
	v_cvt_pk_bf16_f32 v158, v162, v163
	v_cvt_pk_bf16_f32 v159, v164, v165
	ds_write_b128 v244, v[156:159]
	v_lshl_add_u64 v[178:179], v[166:167], 0, v[252:253]
	ds_read_b128 v[172:175], v245
	s_waitcnt lgkmcnt(4)
	global_store_dwordx4 v[186:187], v[182:185], off
	v_pk_mul_f32 v[160:161], v[56:57], s[92:93] op_sel_hi:[1,0]
	v_pk_mul_f32 v[162:163], v[46:47], s[92:93] op_sel_hi:[1,0]
	v_pk_mul_f32 v[158:159], v[54:55], s[92:93] op_sel_hi:[1,0]
	v_pk_mul_f32 v[164:165], v[48:49], s[92:93] op_sel_hi:[1,0]
	v_exp_f32_e32 v158, v158
	v_exp_f32_e32 v159, v159
	v_exp_f32_e32 v160, v160
	v_exp_f32_e32 v161, v161
	v_exp_f32_e32 v162, v162
	v_exp_f32_e32 v163, v163
	v_exp_f32_e32 v164, v164
	v_exp_f32_e32 v165, v165
	v_pk_add_f32 v[158:159], v[158:159], 1.0 op_sel_hi:[1,0]
	v_pk_add_f32 v[160:161], v[160:161], 1.0 op_sel_hi:[1,0]
	v_rcp_f32_e32 v158, v158
	v_rcp_f32_e32 v159, v159
	v_pk_add_f32 v[162:163], v[162:163], 1.0 op_sel_hi:[1,0]
	v_pk_add_f32 v[164:165], v[164:165], 1.0 op_sel_hi:[1,0]
	v_rcp_f32_e32 v160, v160
	v_rcp_f32_e32 v161, v161
	v_rcp_f32_e32 v162, v162
	v_rcp_f32_e32 v163, v163
	v_rcp_f32_e32 v164, v164
	v_rcp_f32_e32 v165, v165
	v_mad_i64_i32 v[156:157], s[18:19], s20, v151, 0
	v_pk_mul_f32 v[158:159], v[54:55], v[158:159]
	v_lshl_add_u64 v[156:157], v[156:157], 1, s[8:9]
	v_pk_mul_f32 v[158:159], v[34:35], v[158:159]
	v_pk_mul_f32 v[160:161], v[56:57], v[160:161]
	v_pk_mul_f32 v[162:163], v[46:47], v[162:163]
	v_pk_mul_f32 v[164:165], v[48:49], v[164:165]
	v_pk_mul_f32 v[160:161], v[36:37], v[160:161]
	v_pk_mul_f32 v[162:163], v[26:27], v[162:163]
	v_pk_mul_f32 v[164:165], v[28:29], v[164:165]
	v_lshl_add_u64 v[166:167], v[156:157], 0, v[142:143]
	v_cvt_pk_bf16_f32 v156, v158, v159
	v_cvt_pk_bf16_f32 v157, v160, v161
	v_cvt_pk_bf16_f32 v158, v162, v163
	v_cvt_pk_bf16_f32 v159, v164, v165
	ds_write_b128 v244, v[156:159]
	v_lshl_add_u64 v[186:187], v[166:167], 0, v[252:253]
	ds_read_b128 v[182:185], v245
	s_waitcnt lgkmcnt(4)
; __device__ __forceinline__ unsigned cvt_pk_bf16(float lo, float hi) { unsigned r; asm volatile("v_cvt_pk_bf16_f32 %0, %1, %2" : "=v"(r) : "v"(lo), "v"(hi)); return r; }
;     __device__ __forceinline__ void operator()(const f32x4 (&acc)[2][2][4][2], const Unit& u, int wr, int wc, int fr, int fq) const {
;     ...
;         const int col0 = u.pn * HALF + wc * 32 + 8 * fq;
; #pragma unroll
;         for (int ai = 0; ai < 2; ++ai)
; #pragma unroll
;             for (int m = 0; m < 4; ++m) { bf16_t* rowp = O + (size_t)(row0 + ai * HALF + m * 16) * ldc + col0;
;                 f32x2 h[4];
; #pragma unroll
;                 for (int n = 0; n < 2; ++n)
; #pragma unroll
;                     for (int j = 0; j < 2; ++j) { const f32x2 g = {acc[ai][0][m][n][2 * j], acc[ai][0][m][n][2 * j + 1]}, up = {acc[ai][1][m][n][2 * j], acc[ai][1][m][n][2 * j + 1]};
;                         const f32x2 t = g * (-1.44269504089f); f32x2 e; e.x = __builtin_amdgcn_exp2f(t.x); e.y = __builtin_amdgcn_exp2f(t.y);
;                         const f32x2 d = e + 1.0f; f32x2 r; r.x = __builtin_amdgcn_rcpf(d.x); r.y = __builtin_amdgcn_rcpf(d.y);
;                         h[n * 2 + j] = (g * r) * up; }
;                 u32x4 w; w.x = cvt_pk_bf16(h[0].x, h[0].y); w.y = cvt_pk_bf16(h[1].x, h[1].y); w.z = cvt_pk_bf16(h[2].x, h[2].y); w.w = cvt_pk_bf16(h[3].x, h[3].y);
;                 *(u32x4*)rowp = w; }
	global_store_dwordx4 v[176:177], v[168:171], off
	v_pk_mul_f32 v[160:161], v[40:41], s[92:93] op_sel_hi:[1,0]
	v_pk_mul_f32 v[162:163], v[30:31], s[92:93] op_sel_hi:[1,0]
	v_pk_mul_f32 v[158:159], v[38:39], s[92:93] op_sel_hi:[1,0]
	v_pk_mul_f32 v[164:165], v[32:33], s[92:93] op_sel_hi:[1,0]
	v_exp_f32_e32 v158, v158
	v_exp_f32_e32 v159, v159
	v_exp_f32_e32 v160, v160
	v_exp_f32_e32 v161, v161
	v_exp_f32_e32 v162, v162
	v_exp_f32_e32 v163, v163
	v_exp_f32_e32 v164, v164
	v_exp_f32_e32 v165, v165
	v_pk_add_f32 v[158:159], v[158:159], 1.0 op_sel_hi:[1,0]
	v_pk_add_f32 v[160:161], v[160:161], 1.0 op_sel_hi:[1,0]
	v_rcp_f32_e32 v158, v158
	v_rcp_f32_e32 v159, v159
	v_pk_add_f32 v[162:163], v[162:163], 1.0 op_sel_hi:[1,0]
	v_pk_add_f32 v[164:165], v[164:165], 1.0 op_sel_hi:[1,0]
	v_rcp_f32_e32 v160, v160
	v_rcp_f32_e32 v161, v161
	v_rcp_f32_e32 v162, v162
	v_rcp_f32_e32 v163, v163
	v_rcp_f32_e32 v164, v164
	v_rcp_f32_e32 v165, v165
	v_mad_i64_i32 v[156:157], s[18:19], s20, v150, 0
	v_pk_mul_f32 v[158:159], v[38:39], v[158:159]
	v_lshl_add_u64 v[156:157], v[156:157], 1, s[8:9]
	v_pk_mul_f32 v[158:159], v[18:19], v[158:159]
	v_pk_mul_f32 v[160:161], v[40:41], v[160:161]
	v_pk_mul_f32 v[162:163], v[30:31], v[162:163]
	v_pk_mul_f32 v[164:165], v[32:33], v[164:165]
	v_pk_mul_f32 v[160:161], v[20:21], v[160:161]
	v_pk_mul_f32 v[162:163], v[10:11], v[162:163]
	v_pk_mul_f32 v[164:165], v[12:13], v[164:165]
	v_lshl_add_u64 v[166:167], v[156:157], 0, v[142:143]
	v_cvt_pk_bf16_f32 v156, v158, v159
	v_cvt_pk_bf16_f32 v157, v160, v161
	v_cvt_pk_bf16_f32 v158, v162, v163
	v_cvt_pk_bf16_f32 v159, v164, v165
	ds_write_b128 v244, v[156:159]
	v_lshl_add_u64 v[176:177], v[166:167], 0, v[252:253]
	ds_read_b128 v[168:171], v245
	s_waitcnt lgkmcnt(4)
	global_store_dwordx4 v[178:179], v[172:175], off
	v_pk_mul_f32 v[160:161], v[24:25], s[92:93] op_sel_hi:[1,0]
	v_pk_mul_f32 v[162:163], v[14:15], s[92:93] op_sel_hi:[1,0]
	v_pk_mul_f32 v[158:159], v[22:23], s[92:93] op_sel_hi:[1,0]
	v_pk_mul_f32 v[164:165], v[16:17], s[92:93] op_sel_hi:[1,0]
	v_exp_f32_e32 v158, v158
	v_exp_f32_e32 v159, v159
	v_exp_f32_e32 v160, v160
	v_exp_f32_e32 v161, v161
	v_exp_f32_e32 v162, v162
	v_exp_f32_e32 v163, v163
	v_exp_f32_e32 v164, v164
	v_exp_f32_e32 v165, v165
	v_pk_add_f32 v[158:159], v[158:159], 1.0 op_sel_hi:[1,0]
	v_pk_add_f32 v[160:161], v[160:161], 1.0 op_sel_hi:[1,0]
	v_rcp_f32_e32 v158, v158
	v_rcp_f32_e32 v159, v159
	v_pk_add_f32 v[162:163], v[162:163], 1.0 op_sel_hi:[1,0]
	v_pk_add_f32 v[164:165], v[164:165], 1.0 op_sel_hi:[1,0]
	v_rcp_f32_e32 v160, v160
	v_rcp_f32_e32 v161, v161
	v_rcp_f32_e32 v162, v162
	v_rcp_f32_e32 v163, v163
	v_rcp_f32_e32 v164, v164
	v_rcp_f32_e32 v165, v165
	v_mad_i64_i32 v[156:157], s[18:19], s20, v149, 0
	v_lshl_add_u64 v[156:157], v[156:157], 1, s[8:9]
	v_pk_mul_f32 v[158:159], v[22:23], v[158:159]
	v_pk_mul_f32 v[160:161], v[24:25], v[160:161]
	v_pk_mul_f32 v[158:159], v[6:7], v[158:159]
	v_pk_mul_f32 v[162:163], v[14:15], v[162:163]
	v_pk_mul_f32 v[164:165], v[16:17], v[164:165]
	v_lshl_add_u64 v[142:143], v[156:157], 0, v[142:143]
	v_pk_mul_f32 v[160:161], v[8:9], v[160:161]
	v_pk_mul_f32 v[162:163], v[2:3], v[162:163]
	v_pk_mul_f32 v[164:165], v[4:5], v[164:165]
	v_cvt_pk_bf16_f32 v156, v158, v159
	v_cvt_pk_bf16_f32 v157, v160, v161
	v_cvt_pk_bf16_f32 v158, v162, v163
	s_mov_b64 s[38:39], 0
	v_cvt_pk_bf16_f32 v159, v164, v165
	ds_write_b128 v244, v[156:159]
	v_lshl_add_u64 v[178:179], v[142:143], 0, v[252:253]
	ds_read_b128 v[172:175], v245
	s_waitcnt lgkmcnt(4)
	global_store_dwordx4 v[186:187], v[182:185], off
	s_waitcnt lgkmcnt(2)
	global_store_dwordx4 v[176:177], v[168:171], off
	s_waitcnt lgkmcnt(0)
	global_store_dwordx4 v[178:179], v[172:175], off
; __device__ __forceinline__ unsigned cvt_pk_bf16(float lo, float hi) { unsigned r; asm volatile("v_cvt_pk_bf16_f32 %0, %1, %2" : "=v"(r) : "v"(lo), "v"(hi)); return r; }
;     __device__ __forceinline__ void operator()(const f32x4 (&acc)[2][2][4][2], const Unit& u, int wr, int wc, int fr, int fq) const {
;     ...
;         if (!swiglu) {
;             const int col0 = u.pn * BM + wc * 32 + 8 * fq;
; #pragma unroll
;             for (int ai = 0; ai < 2; ++ai)
; #pragma unroll
;                 for (int m = 0; m < 4; ++m) { bf16_t* rowp = O + (size_t)(row0 + ai * HALF + m * 16) * ldc + col0;
; #pragma unroll
;                     for (int bj = 0; bj < 2; ++bj) { const f32x4 v0 = acc[ai][bj][m][0], v1 = acc[ai][bj][m][1];
;                         u32x4 w; w.x = cvt_pk_bf16(v0[0], v0[1]); w.y = cvt_pk_bf16(v0[2], v0[3]); w.z = cvt_pk_bf16(v1[0], v1[1]); w.w = cvt_pk_bf16(v1[2], v1[3]);
;                         *(u32x4*)(rowp + bj * HALF) = w; } }
;             return;
.LBB0_365:
	s_andn2_b64 vcc, exec, s[38:39]
	s_cbranch_vccnz .LBB0_367
	v_lshl_or_b32 v142, s67, 8, v146
	v_ashrrev_i32_e32 v143, 31, v142
	v_lshlrev_b64 v[142:143], 1, v[142:143]
	v_lshl_add_u64 v[140:141], v[140:141], 0, v[142:143]
	v_cvt_pk_bf16_f32 v156, v126, v127
	v_cvt_pk_bf16_f32 v157, v128, v129
	v_cvt_pk_bf16_f32 v158, v122, v123
	v_cvt_pk_bf16_f32 v159, v124, v125
	ds_write_b128 v244, v[156:159]
	v_lshl_add_u64 v[176:177], v[140:141], 0, v[252:253]
	ds_read_b128 v[168:171], v245
	s_nop 1
	v_cvt_pk_bf16_f32 v156, v114, v115
	v_cvt_pk_bf16_f32 v157, v116, v117
	v_cvt_pk_bf16_f32 v158, v106, v107
	v_cvt_pk_bf16_f32 v159, v108, v109
	ds_write_b128 v244, v[156:159]
	v_lshl_add_u64 v[178:179], v[140:141], 0, v[252:253]
	ds_read_b128 v[172:175], v245
	v_mad_i64_i32 v[140:141], s[18:19], s20, v155, 0
	v_lshl_add_u64 v[140:141], v[140:141], 1, s[8:9]
	v_lshl_add_u64 v[140:141], v[140:141], 0, v[142:143]
	v_cvt_pk_bf16_f32 v156, v118, v119
	v_cvt_pk_bf16_f32 v157, v120, v121
	v_cvt_pk_bf16_f32 v158, v110, v111
	v_cvt_pk_bf16_f32 v159, v112, v113
	ds_write_b128 v244, v[156:159]
	v_lshl_add_u64 v[186:187], v[140:141], 0, v[252:253]
	ds_read_b128 v[182:185], v245
	s_waitcnt lgkmcnt(4)
	global_store_dwordx4 v[176:177], v[168:171], off
	s_nop 1
	v_cvt_pk_bf16_f32 v156, v98, v99
	v_cvt_pk_bf16_f32 v157, v100, v101
	v_cvt_pk_bf16_f32 v158, v90, v91
	v_cvt_pk_bf16_f32 v159, v92, v93
	ds_write_b128 v244, v[156:159]
	v_lshl_add_u64 v[176:177], v[140:141], 0, v[252:253]
	ds_read_b128 v[168:171], v245
	s_waitcnt lgkmcnt(4)
	global_store_dwordx4 v[178:179], v[172:175], off offset:256
	v_mad_i64_i32 v[140:141], s[18:19], s20, v154, 0
	v_lshl_add_u64 v[140:141], v[140:141], 1, s[8:9]
	v_lshl_add_u64 v[140:141], v[140:141], 0, v[142:143]
	v_cvt_pk_bf16_f32 v154, v102, v103
	v_cvt_pk_bf16_f32 v155, v104, v105
	v_cvt_pk_bf16_f32 v156, v94, v95
	v_cvt_pk_bf16_f32 v157, v96, v97
	ds_write_b128 v244, v[154:157]
	v_lshl_add_u64 v[178:179], v[140:141], 0, v[252:253]
	ds_read_b128 v[172:175], v245
	s_waitcnt lgkmcnt(4)
	global_store_dwordx4 v[186:187], v[182:185], off
	s_nop 1
	v_cvt_pk_bf16_f32 v154, v82, v83
	v_cvt_pk_bf16_f32 v155, v84, v85
	v_cvt_pk_bf16_f32 v156, v74, v75
	v_cvt_pk_bf16_f32 v157, v76, v77
	ds_write_b128 v244, v[154:157]
	v_lshl_add_u64 v[186:187], v[140:141], 0, v[252:253]
	ds_read_b128 v[182:185], v245
	s_waitcnt lgkmcnt(4)
	global_store_dwordx4 v[176:177], v[168:171], off offset:256
	v_mad_i64_i32 v[140:141], s[18:19], s20, v153, 0
	v_lshl_add_u64 v[140:141], v[140:141], 1, s[8:9]
	v_lshl_add_u64 v[140:141], v[140:141], 0, v[142:143]
	v_cvt_pk_bf16_f32 v154, v86, v87
	v_cvt_pk_bf16_f32 v155, v88, v89
	v_cvt_pk_bf16_f32 v156, v78, v79
	v_cvt_pk_bf16_f32 v157, v80, v81
	ds_write_b128 v244, v[154:157]
	v_lshl_add_u64 v[176:177], v[140:141], 0, v[252:253]
	ds_read_b128 v[168:171], v245
	s_waitcnt lgkmcnt(4)
	global_store_dwordx4 v[178:179], v[172:175], off
	s_nop 1
	v_cvt_pk_bf16_f32 v154, v70, v71
	v_cvt_pk_bf16_f32 v155, v72, v73
	v_cvt_pk_bf16_f32 v156, v66, v67
	v_cvt_pk_bf16_f32 v157, v68, v69
	ds_write_b128 v244, v[154:157]
	v_lshl_add_u64 v[178:179], v[140:141], 0, v[252:253]
	ds_read_b128 v[172:175], v245
	s_waitcnt lgkmcnt(4)
	global_store_dwordx4 v[186:187], v[182:185], off offset:256
	v_mad_i64_i32 v[140:141], s[18:19], s20, v152, 0
	v_lshl_add_u64 v[140:141], v[140:141], 1, s[8:9]
	v_lshl_add_u64 v[140:141], v[140:141], 0, v[142:143]
	v_cvt_pk_bf16_f32 v152, v62, v63
	v_cvt_pk_bf16_f32 v153, v64, v65
	v_cvt_pk_bf16_f32 v154, v58, v59
	v_cvt_pk_bf16_f32 v155, v60, v61
	ds_write_b128 v244, v[152:155]
	v_lshl_add_u64 v[186:187], v[140:141], 0, v[252:253]
	ds_read_b128 v[182:185], v245
	s_waitcnt lgkmcnt(4)
	global_store_dwordx4 v[176:177], v[168:171], off
	s_nop 1
	v_cvt_pk_bf16_f32 v152, v50, v51
	v_cvt_pk_bf16_f32 v153, v52, v53
	v_cvt_pk_bf16_f32 v154, v42, v43
	v_cvt_pk_bf16_f32 v155, v44, v45
	ds_write_b128 v244, v[152:155]
	v_lshl_add_u64 v[176:177], v[140:141], 0, v[252:253]
	ds_read_b128 v[168:171], v245
	s_waitcnt lgkmcnt(4)
	global_store_dwordx4 v[178:179], v[172:175], off offset:256
	v_mad_i64_i32 v[140:141], s[18:19], s20, v151, 0
	v_lshl_add_u64 v[140:141], v[140:141], 1, s[8:9]
	v_lshl_add_u64 v[140:141], v[140:141], 0, v[142:143]
	v_cvt_pk_bf16_f32 v152, v54, v55
	v_cvt_pk_bf16_f32 v153, v56, v57
	v_cvt_pk_bf16_f32 v154, v46, v47
	v_cvt_pk_bf16_f32 v155, v48, v49
	ds_write_b128 v244, v[152:155]
	v_lshl_add_u64 v[178:179], v[140:141], 0, v[252:253]
	ds_read_b128 v[172:175], v245
	s_waitcnt lgkmcnt(4)
	global_store_dwordx4 v[186:187], v[182:185], off
	s_nop 1
	v_cvt_pk_bf16_f32 v152, v34, v35
	v_cvt_pk_bf16_f32 v153, v36, v37
	v_cvt_pk_bf16_f32 v154, v26, v27
	v_cvt_pk_bf16_f32 v155, v28, v29
	ds_write_b128 v244, v[152:155]
	v_lshl_add_u64 v[186:187], v[140:141], 0, v[252:253]
	ds_read_b128 v[182:185], v245
	s_waitcnt lgkmcnt(4)
	global_store_dwordx4 v[176:177], v[168:171], off offset:256
	v_mad_i64_i32 v[140:141], s[18:19], s20, v150, 0
	v_lshl_add_u64 v[140:141], v[140:141], 1, s[8:9]
	v_lshl_add_u64 v[140:141], v[140:141], 0, v[142:143]
	v_cvt_pk_bf16_f32 v150, v38, v39
	v_cvt_pk_bf16_f32 v151, v40, v41
	v_cvt_pk_bf16_f32 v152, v30, v31
	v_cvt_pk_bf16_f32 v153, v32, v33
	ds_write_b128 v244, v[150:153]
	v_lshl_add_u64 v[176:177], v[140:141], 0, v[252:253]
	ds_read_b128 v[168:171], v245
	s_waitcnt lgkmcnt(4)
	global_store_dwordx4 v[178:179], v[172:175], off
	s_nop 1
	v_cvt_pk_bf16_f32 v150, v18, v19
	v_cvt_pk_bf16_f32 v151, v20, v21
	v_cvt_pk_bf16_f32 v152, v10, v11
	v_cvt_pk_bf16_f32 v153, v12, v13
	ds_write_b128 v244, v[150:153]
	v_lshl_add_u64 v[178:179], v[140:141], 0, v[252:253]
	ds_read_b128 v[172:175], v245
	s_waitcnt lgkmcnt(4)
	global_store_dwordx4 v[186:187], v[182:185], off offset:256
	v_mad_i64_i32 v[140:141], s[18:19], s20, v149, 0
	v_lshl_add_u64 v[140:141], v[140:141], 1, s[8:9]
	v_lshl_add_u64 v[150:151], v[140:141], 0, v[142:143]
	v_cvt_pk_bf16_f32 v140, v22, v23
	v_cvt_pk_bf16_f32 v141, v24, v25
	v_cvt_pk_bf16_f32 v142, v14, v15
	v_cvt_pk_bf16_f32 v143, v16, v17
	ds_write_b128 v244, v[140:143]
	v_lshl_add_u64 v[186:187], v[150:151], 0, v[252:253]
	ds_read_b128 v[182:185], v245
	s_waitcnt lgkmcnt(4)
	global_store_dwordx4 v[176:177], v[168:171], off
	s_nop 1
	v_cvt_pk_bf16_f32 v140, v6, v7
	v_cvt_pk_bf16_f32 v141, v8, v9
	v_cvt_pk_bf16_f32 v142, v2, v3
	v_cvt_pk_bf16_f32 v143, v4, v5
	ds_write_b128 v244, v[140:143]
	v_lshl_add_u64 v[176:177], v[150:151], 0, v[252:253]
	ds_read_b128 v[168:171], v245
	s_waitcnt lgkmcnt(4)
	global_store_dwordx4 v[178:179], v[172:175], off offset:256
	s_waitcnt lgkmcnt(2)
	global_store_dwordx4 v[186:187], v[182:185], off
	s_waitcnt lgkmcnt(0)
	global_store_dwordx4 v[176:177], v[168:171], off offset:256

; __device__ __forceinline__ unsigned cvt_pk_bf16(float lo, float hi) { unsigned r; asm volatile("v_cvt_pk_bf16_f32 %0, %1, %2" : "=v"(r) : "v"(lo), "v"(hi)); return r; }
;     __device__ __forceinline__ void operator()(const f32x4 (&acc)[2][2][4][2], const Unit& u, int wr, int wc, int fr, int fq) const {
;     ...
;         if (u.part >= 0) {
;             bf16_t* Pp = P + (size_t)u.part * pstride; const int col0 = u.pn * BM + wc * 32 + 8 * fq;
; #pragma unroll
;             for (int ai = 0; ai < 2; ++ai)
; #pragma unroll
;                 for (int m = 0; m < 4; ++m) { bf16_t* rowp = Pp + (size_t)(row0 + ai * HALF + m * 16 - prow0) * ldc + col0;
; #pragma unroll
;                     for (int bj = 0; bj < 2; ++bj) { const f32x4 v0 = acc[ai][bj][m][0], v1 = acc[ai][bj][m][1];
;                         u32x4 w; w.x = cvt_pk_bf16(v0[0], v0[1]); w.y = cvt_pk_bf16(v0[2], v0[3]); w.z = cvt_pk_bf16(v1[0], v1[1]); w.w = cvt_pk_bf16(v1[2], v1[3]);
;                         *(u32x4*)(rowp + bj * HALF) = w; } }
;             return;
.LBB0_370:
	s_mov_b32 s31, s89
	s_lshl_b64 s[18:19], s[30:31], 23
	s_add_u32 s18, s70, s18
	v_lshl_or_b32 v140, s67, 8, v146
	s_addc_u32 s19, s71, s19
	v_ashrrev_i32_e32 v141, 31, v140
	v_add_u32_e32 v142, 0xffffc000, v148
	v_lshl_add_u64 v[140:141], v[140:141], 1, s[18:19]
	v_mad_i64_i32 v[142:143], s[18:19], s20, v142, 0
	v_lshl_add_u64 v[142:143], v[142:143], 1, v[140:141]
	v_cvt_pk_bf16_f32 v126, v126, v127
	v_cvt_pk_bf16_f32 v127, v128, v129
	v_cvt_pk_bf16_f32 v128, v122, v123
	v_cvt_pk_bf16_f32 v129, v124, v125
	ds_write_b128 v244, v[126:129]
	v_lshl_add_u64 v[176:177], v[142:143], 0, v[252:253]
	ds_read_b128 v[168:171], v245
	v_cvt_pk_bf16_f32 v114, v114, v115
	v_cvt_pk_bf16_f32 v115, v116, v117
	v_cvt_pk_bf16_f32 v116, v106, v107
	v_add_u32_e32 v106, 0xffffc010, v148
	v_mad_i64_i32 v[106:107], s[18:19], s20, v106, 0
	v_cvt_pk_bf16_f32 v117, v108, v109
	ds_write_b128 v244, v[114:117]
	v_lshl_add_u64 v[178:179], v[142:143], 0, v[252:253]
	ds_read_b128 v[172:175], v245
	s_nop 1
	v_lshl_add_u64 v[114:115], v[106:107], 1, v[140:141]
	v_cvt_pk_bf16_f32 v106, v118, v119
	v_cvt_pk_bf16_f32 v107, v120, v121
	v_cvt_pk_bf16_f32 v108, v110, v111
	v_cvt_pk_bf16_f32 v109, v112, v113
	ds_write_b128 v244, v[106:109]
	v_lshl_add_u64 v[186:187], v[114:115], 0, v[252:253]
	ds_read_b128 v[182:185], v245
	s_waitcnt lgkmcnt(4)
	global_store_dwordx4 v[176:177], v[168:171], off
	v_cvt_pk_bf16_f32 v98, v98, v99
	v_cvt_pk_bf16_f32 v99, v100, v101
	v_cvt_pk_bf16_f32 v100, v90, v91
	v_add_u32_e32 v90, 0xffffc020, v148
	v_mad_i64_i32 v[90:91], s[18:19], s20, v90, 0
	v_cvt_pk_bf16_f32 v101, v92, v93
	ds_write_b128 v244, v[98:101]
	v_lshl_add_u64 v[176:177], v[114:115], 0, v[252:253]
	ds_read_b128 v[168:171], v245
	s_waitcnt lgkmcnt(4)
	global_store_dwordx4 v[178:179], v[172:175], off offset:256
	s_nop 1
	v_lshl_add_u64 v[98:99], v[90:91], 1, v[140:141]
	v_cvt_pk_bf16_f32 v90, v102, v103
	v_cvt_pk_bf16_f32 v91, v104, v105
	v_cvt_pk_bf16_f32 v92, v94, v95
	v_cvt_pk_bf16_f32 v93, v96, v97
	ds_write_b128 v244, v[90:93]
	v_lshl_add_u64 v[178:179], v[98:99], 0, v[252:253]
	ds_read_b128 v[172:175], v245
	s_waitcnt lgkmcnt(4)
	global_store_dwordx4 v[186:187], v[182:185], off
	v_cvt_pk_bf16_f32 v82, v82, v83
	v_cvt_pk_bf16_f32 v83, v84, v85
	v_cvt_pk_bf16_f32 v84, v74, v75
	v_add_u32_e32 v74, 0xffffc030, v148
	v_mad_i64_i32 v[74:75], s[18:19], s20, v74, 0
	v_cvt_pk_bf16_f32 v85, v76, v77
	ds_write_b128 v244, v[82:85]
	v_lshl_add_u64 v[186:187], v[98:99], 0, v[252:253]
	ds_read_b128 v[182:185], v245
	s_waitcnt lgkmcnt(4)
	global_store_dwordx4 v[176:177], v[168:171], off offset:256
	s_nop 1
	v_lshl_add_u64 v[82:83], v[74:75], 1, v[140:141]
	v_cvt_pk_bf16_f32 v74, v86, v87
	v_cvt_pk_bf16_f32 v75, v88, v89
	v_cvt_pk_bf16_f32 v76, v78, v79
	v_cvt_pk_bf16_f32 v77, v80, v81
	ds_write_b128 v244, v[74:77]
	v_lshl_add_u64 v[176:177], v[82:83], 0, v[252:253]
	ds_read_b128 v[168:171], v245
	s_waitcnt lgkmcnt(4)
	global_store_dwordx4 v[178:179], v[172:175], off
	v_cvt_pk_bf16_f32 v70, v70, v71
	v_cvt_pk_bf16_f32 v71, v72, v73
	v_cvt_pk_bf16_f32 v72, v66, v67
	v_add_u32_e32 v66, 0xffffc080, v148
	v_mad_i64_i32 v[66:67], s[18:19], s20, v66, 0
	v_lshl_add_u64 v[66:67], v[66:67], 1, v[140:141]
	v_cvt_pk_bf16_f32 v73, v68, v69
	ds_write_b128 v244, v[70:73]
	v_lshl_add_u64 v[178:179], v[82:83], 0, v[252:253]
	ds_read_b128 v[172:175], v245
	s_waitcnt lgkmcnt(4)
	global_store_dwordx4 v[186:187], v[182:185], off offset:256
	v_cvt_pk_bf16_f32 v62, v62, v63
	v_cvt_pk_bf16_f32 v63, v64, v65
	v_cvt_pk_bf16_f32 v64, v58, v59
	v_cvt_pk_bf16_f32 v65, v60, v61
	ds_write_b128 v244, v[62:65]
	v_lshl_add_u64 v[186:187], v[66:67], 0, v[252:253]
	ds_read_b128 v[182:185], v245
	s_waitcnt lgkmcnt(4)
	global_store_dwordx4 v[176:177], v[168:171], off
	v_cvt_pk_bf16_f32 v50, v50, v51
	v_cvt_pk_bf16_f32 v51, v52, v53
	v_cvt_pk_bf16_f32 v52, v42, v43
	v_add_u32_e32 v42, 0xffffc090, v148
	v_mad_i64_i32 v[42:43], s[18:19], s20, v42, 0
	v_cvt_pk_bf16_f32 v53, v44, v45
	ds_write_b128 v244, v[50:53]
	v_lshl_add_u64 v[176:177], v[66:67], 0, v[252:253]
	ds_read_b128 v[168:171], v245
	s_waitcnt lgkmcnt(4)
	global_store_dwordx4 v[178:179], v[172:175], off offset:256
	s_nop 1
	v_lshl_add_u64 v[50:51], v[42:43], 1, v[140:141]
	v_cvt_pk_bf16_f32 v42, v54, v55
	v_cvt_pk_bf16_f32 v43, v56, v57
	v_cvt_pk_bf16_f32 v44, v46, v47
	v_cvt_pk_bf16_f32 v45, v48, v49
	ds_write_b128 v244, v[42:45]
	v_lshl_add_u64 v[178:179], v[50:51], 0, v[252:253]
	ds_read_b128 v[172:175], v245
	s_waitcnt lgkmcnt(4)
	global_store_dwordx4 v[186:187], v[182:185], off
	v_cvt_pk_bf16_f32 v34, v34, v35
	v_cvt_pk_bf16_f32 v35, v36, v37
	v_cvt_pk_bf16_f32 v36, v26, v27
	v_add_u32_e32 v26, 0xffffc0a0, v148
	v_mad_i64_i32 v[26:27], s[18:19], s20, v26, 0
	v_cvt_pk_bf16_f32 v37, v28, v29
	ds_write_b128 v244, v[34:37]
	v_lshl_add_u64 v[186:187], v[50:51], 0, v[252:253]
	ds_read_b128 v[182:185], v245
	s_waitcnt lgkmcnt(4)
	global_store_dwordx4 v[176:177], v[168:171], off offset:256
	s_nop 1
	v_lshl_add_u64 v[34:35], v[26:27], 1, v[140:141]
	v_cvt_pk_bf16_f32 v26, v38, v39
	v_cvt_pk_bf16_f32 v27, v40, v41
	v_cvt_pk_bf16_f32 v28, v30, v31
	v_cvt_pk_bf16_f32 v29, v32, v33
	ds_write_b128 v244, v[26:29]
	v_lshl_add_u64 v[176:177], v[34:35], 0, v[252:253]
	ds_read_b128 v[168:171], v245
	s_waitcnt lgkmcnt(4)
	global_store_dwordx4 v[178:179], v[172:175], off
	v_cvt_pk_bf16_f32 v18, v18, v19
	v_cvt_pk_bf16_f32 v19, v20, v21
	v_cvt_pk_bf16_f32 v20, v10, v11
	v_add_u32_e32 v10, 0xffffc0b0, v148
	v_mad_i64_i32 v[10:11], s[18:19], s20, v10, 0
	v_cvt_pk_bf16_f32 v21, v12, v13
	ds_write_b128 v244, v[18:21]
	v_lshl_add_u64 v[178:179], v[34:35], 0, v[252:253]
	ds_read_b128 v[172:175], v245
	s_waitcnt lgkmcnt(4)
	global_store_dwordx4 v[186:187], v[182:185], off offset:256
	s_nop 1
	v_lshl_add_u64 v[18:19], v[10:11], 1, v[140:141]
	v_cvt_pk_bf16_f32 v10, v22, v23
	v_cvt_pk_bf16_f32 v11, v24, v25
	v_cvt_pk_bf16_f32 v12, v14, v15
	v_cvt_pk_bf16_f32 v13, v16, v17
	ds_write_b128 v244, v[10:13]
	v_lshl_add_u64 v[186:187], v[18:19], 0, v[252:253]
	ds_read_b128 v[182:185], v245
	s_waitcnt lgkmcnt(4)
	global_store_dwordx4 v[176:177], v[168:171], off
	v_cvt_pk_bf16_f32 v6, v6, v7
	v_cvt_pk_bf16_f32 v7, v8, v9
	v_cvt_pk_bf16_f32 v8, v2, v3
	v_cvt_pk_bf16_f32 v9, v4, v5
	ds_write_b128 v244, v[6:9]
	v_lshl_add_u64 v[176:177], v[18:19], 0, v[252:253]
	ds_read_b128 v[168:171], v245
	s_waitcnt lgkmcnt(4)
	global_store_dwordx4 v[178:179], v[172:175], off offset:256
	s_and_b64 vcc, exec, s[40:41]
	s_mov_b64 s[30:31], -1
	s_waitcnt lgkmcnt(2)
	global_store_dwordx4 v[186:187], v[182:185], off
	s_waitcnt lgkmcnt(0)
	global_store_dwordx4 v[176:177], v[168:171], off offset:256
	s_cbranch_vccnz .LBB0_345
